# attention row-max chain: removed redundant canonicalizing v_max x,x,x ops (5 sites), on top of v12
# speedup vs baseline: 1.0093x; 1.0041x over previous
.LBB0_77:
	v_mfma_f32_32x32x16_bf16 v[80:95], v[176:179], v[136:139], 0
	v_mfma_f32_32x32x16_bf16 v[64:79], v[168:171], v[136:139], 0
	v_add_u32_e32 v96, s18, v231
	ds_read_b64_tr_b16 v[168:169], v96 offset:24576
	ds_read_b64_tr_b16 v[170:171], v96 offset:25088
	s_waitcnt lgkmcnt(9)
	v_mfma_f32_32x32x16_bf16 v[80:95], v[172:175], v[132:135], v[80:95]
	v_add_f32_e32 v97, v48, v49
	v_add_f32_e32 v97, v50, v97
	v_add_f32_e32 v97, v51, v97
	v_add_f32_e32 v97, v52, v97
	v_add_f32_e32 v97, v53, v97
	v_cvt_pk_bf16_f32 v128, v48, v49
	v_cvt_pk_bf16_f32 v129, v50, v51
	ds_read_b64_tr_b16 v[172:173], v96 offset:28672
	ds_read_b64_tr_b16 v[174:175], v96 offset:29184
	s_waitcnt lgkmcnt(10)
	v_mfma_f32_32x32x16_bf16 v[64:79], v[164:167], v[132:135], v[64:79]
	v_add_f32_e32 v48, v54, v97
	v_add_f32_e32 v48, v55, v48
	v_add_f32_e32 v48, v56, v48
	v_add_f32_e32 v97, v57, v48
	v_cvt_pk_bf16_f32 v130, v52, v53
	v_cvt_pk_bf16_f32 v131, v54, v55
	ds_read_b64_tr_b16 v[48:49], v96 offset:25600
	ds_read_b64_tr_b16 v[50:51], v96 offset:26112
	s_waitcnt lgkmcnt(11)
	v_mfma_f32_32x32x16_bf16 v[80:95], v[160:163], v[124:127], v[80:95]
	v_add_f32_e32 v52, v58, v97
	v_add_f32_e32 v52, v59, v52
	v_add_f32_e32 v52, v60, v52
	v_add_f32_e32 v97, v61, v52
	v_cvt_pk_bf16_f32 v120, v56, v57
	v_cvt_pk_bf16_f32 v121, v58, v59
	ds_read_b64_tr_b16 v[52:53], v96 offset:29696
	ds_read_b64_tr_b16 v[54:55], v96 offset:30208
	s_waitcnt lgkmcnt(12)
	v_mfma_f32_32x32x16_bf16 v[64:79], v[156:159], v[124:127], v[64:79]
	v_add_f32_e32 v56, v62, v97
	v_add_f32_e32 v56, v63, v56
	v_add_f32_e32 v56, v32, v56
	v_add_f32_e32 v97, v33, v56
	v_cvt_pk_bf16_f32 v122, v60, v61
	v_cvt_pk_bf16_f32 v123, v62, v63
	ds_read_b64_tr_b16 v[56:57], v96 offset:26624
	ds_read_b64_tr_b16 v[58:59], v96 offset:27136
	s_waitcnt lgkmcnt(13)
	v_mfma_f32_32x32x16_bf16 v[80:95], v[152:155], v[116:119], v[80:95]
	v_add_f32_e32 v60, v34, v97
	v_add_f32_e32 v60, v35, v60
	v_add_f32_e32 v60, v36, v60
	v_add_f32_e32 v60, v37, v60
	v_cvt_pk_bf16_f32 v112, v32, v33
	v_cvt_pk_bf16_f32 v113, v34, v35
	ds_read_b64_tr_b16 v[32:33], v96 offset:30720
	ds_read_b64_tr_b16 v[34:35], v96 offset:31232
	s_waitcnt lgkmcnt(14)
	v_mfma_f32_32x32x16_bf16 v[64:79], v[148:151], v[116:119], v[64:79]
	v_add_f32_e32 v60, v38, v60
	v_add_f32_e32 v60, v39, v60
	v_add_f32_e32 v60, v40, v60
	v_add_f32_e32 v60, v41, v60
	v_cvt_pk_bf16_f32 v114, v36, v37
	v_cvt_pk_bf16_f32 v115, v38, v39
	ds_read_b64_tr_b16 v[36:37], v96 offset:27648
	ds_read_b64_tr_b16 v[38:39], v96 offset:28160
	s_waitcnt lgkmcnt(14)
	v_mfma_f32_32x32x16_bf16 v[80:95], v[144:147], v[108:111], v[80:95]
	v_add_f32_e32 v60, v42, v60
	v_add_f32_e32 v60, v43, v60
	v_add_f32_e32 v60, v44, v60
	v_add_f32_e32 v60, v45, v60
	v_cvt_pk_bf16_f32 v104, v40, v41
	v_cvt_pk_bf16_f32 v105, v42, v43
	ds_read_b64_tr_b16 v[40:41], v96 offset:31744
	ds_read_b64_tr_b16 v[42:43], v96 offset:32256
	v_mfma_f32_32x32x16_bf16 v[64:79], v[140:143], v[108:111], v[64:79]
	v_add_f32_e32 v60, v46, v60
	v_add_f32_e32 v60, v47, v60
	v_add_f32_e32 v60, 0, v60
	v_cvt_pk_bf16_f32 v106, v44, v45
	v_cvt_pk_bf16_f32 v107, v46, v47
	v_lshl_add_u64 v[176:177], v[186:187], 0, s[12:13]
	v_lshl_add_u64 v[44:45], v[176:177], 0, s[70:71]
	v_lshl_add_u64 v[178:179], v[184:185], 0, s[12:13]
	s_add_i32 s18, s50, s42
	s_mov_b32 s19, m0
	s_mov_b32 m0, s18
	s_nop 0
	global_load_lds_dwordx4 v[44:45], off
	s_mov_b32 m0, s19
	v_lshl_add_u64 v[44:45], v[178:179], 0, s[78:79]
	s_add_i32 s18, s48, s43
	s_mov_b32 s19, m0
	s_mov_b32 m0, s18
	s_nop 0
	global_load_lds_dwordx4 v[44:45], off
	s_mov_b32 m0, s19
	v_max_f32_e32 v44, v80, v81
	v_max3_f32 v45, v82, v83, v65
	v_max3_f32 v44, v44, v64, v66
	v_max3_f32 v44, v44, v67, v84
	v_max3_f32 v45, v45, v86, v87
	v_max3_f32 v44, v44, v85, v68
	v_max3_f32 v45, v45, v70, v71
	v_max3_f32 v44, v44, v69, v88
	v_max3_f32 v45, v45, v90, v91
	v_max3_f32 v44, v44, v89, v72
	v_max3_f32 v45, v45, v74, v75
	v_max3_f32 v44, v44, v73, v92
	v_max3_f32 v45, v45, v94, v95
	v_max3_f32 v44, v44, v93, v76
	v_max3_f32 v45, v45, v78, v79
	v_max3_f32 v44, v44, v77, v45
	v_mov_b32_e32 v45, v44
	s_nop 1
	v_permlane32_swap_b32_e32 v44, v45
	v_max_f32_e32 v44, v44, v45
	v_cmp_lt_f32_e32 vcc, s58, v44
	s_cmp_lg_u64 vcc, 0
	v_add_f32_e32 v183, v234, v60
	s_cselect_b64 s[18:19], -1, 0
	s_cbranch_vccnz .LBB0_85

.LBB0_80:
	s_add_i32 s18, s48, 0x2000
	s_cmpk_lg_i32 s48, 0x4000
	s_cselect_b32 s45, s18, 0
	v_mfma_f32_32x32x16_bf16 v[48:63], v[60:63], v[136:139], 0
	v_mfma_f32_32x32x16_bf16 v[32:47], v[44:47], v[136:139], 0
	v_add_u32_e32 v96, s50, v231
	ds_read_b64_tr_b16 v[140:141], v96 offset:24576
	ds_read_b64_tr_b16 v[142:143], v96 offset:25088
	s_waitcnt lgkmcnt(9)
	v_mfma_f32_32x32x16_bf16 v[48:63], v[144:147], v[132:135], v[48:63]
	v_add_f32_e32 v97, v80, v81
	v_add_f32_e32 v97, v82, v97
	v_add_f32_e32 v97, v83, v97
	v_add_f32_e32 v97, v84, v97
	v_add_f32_e32 v97, v85, v97
	v_cvt_pk_bf16_f32 v128, v80, v81
	v_cvt_pk_bf16_f32 v129, v82, v83
	ds_read_b64_tr_b16 v[144:145], v96 offset:28672
	ds_read_b64_tr_b16 v[146:147], v96 offset:29184
	s_waitcnt lgkmcnt(10)
	v_mfma_f32_32x32x16_bf16 v[32:47], v[172:175], v[132:135], v[32:47]
	v_add_f32_e32 v80, v86, v97
	v_add_f32_e32 v80, v87, v80
	v_add_f32_e32 v80, v88, v80
	v_add_f32_e32 v97, v89, v80
	v_cvt_pk_bf16_f32 v130, v84, v85
	v_cvt_pk_bf16_f32 v131, v86, v87
	ds_read_b64_tr_b16 v[80:81], v96 offset:25600
	ds_read_b64_tr_b16 v[82:83], v96 offset:26112
	s_waitcnt lgkmcnt(11)
	v_mfma_f32_32x32x16_bf16 v[48:63], v[168:171], v[124:127], v[48:63]
	v_add_f32_e32 v84, v90, v97
	v_add_f32_e32 v84, v91, v84
	v_add_f32_e32 v84, v92, v84
	v_add_f32_e32 v97, v93, v84
	v_cvt_pk_bf16_f32 v120, v88, v89
	v_cvt_pk_bf16_f32 v121, v90, v91
	ds_read_b64_tr_b16 v[84:85], v96 offset:29696
	ds_read_b64_tr_b16 v[86:87], v96 offset:30208
	s_waitcnt lgkmcnt(12)
	v_mfma_f32_32x32x16_bf16 v[32:47], v[164:167], v[124:127], v[32:47]
	v_add_f32_e32 v88, v94, v97
	v_add_f32_e32 v88, v95, v88
	v_add_f32_e32 v88, v64, v88
	v_add_f32_e32 v97, v65, v88
	v_cvt_pk_bf16_f32 v122, v92, v93
	v_cvt_pk_bf16_f32 v123, v94, v95
	ds_read_b64_tr_b16 v[88:89], v96 offset:26624
	ds_read_b64_tr_b16 v[90:91], v96 offset:27136
	s_waitcnt lgkmcnt(13)
	v_mfma_f32_32x32x16_bf16 v[48:63], v[160:163], v[116:119], v[48:63]
	v_add_f32_e32 v92, v66, v97
	v_add_f32_e32 v92, v67, v92
	v_add_f32_e32 v92, v68, v92
	v_add_f32_e32 v92, v69, v92
	v_cvt_pk_bf16_f32 v112, v64, v65
	v_cvt_pk_bf16_f32 v113, v66, v67
	ds_read_b64_tr_b16 v[64:65], v96 offset:30720
	ds_read_b64_tr_b16 v[66:67], v96 offset:31232
	s_waitcnt lgkmcnt(14)
	v_mfma_f32_32x32x16_bf16 v[32:47], v[156:159], v[116:119], v[32:47]
	v_add_f32_e32 v92, v70, v92
	v_add_f32_e32 v92, v71, v92
	v_add_f32_e32 v92, v72, v92
	v_add_f32_e32 v92, v73, v92
	v_cvt_pk_bf16_f32 v114, v68, v69
	v_cvt_pk_bf16_f32 v115, v70, v71
	ds_read_b64_tr_b16 v[68:69], v96 offset:27648
	ds_read_b64_tr_b16 v[70:71], v96 offset:28160
	s_waitcnt lgkmcnt(14)
	v_mfma_f32_32x32x16_bf16 v[48:63], v[152:155], v[108:111], v[48:63]
	v_add_f32_e32 v92, v74, v92
	v_add_f32_e32 v92, v75, v92
	v_add_f32_e32 v92, v76, v92
	v_add_f32_e32 v92, v77, v92
	v_cvt_pk_bf16_f32 v104, v72, v73
	v_cvt_pk_bf16_f32 v105, v74, v75
	ds_read_b64_tr_b16 v[72:73], v96 offset:31744
	ds_read_b64_tr_b16 v[74:75], v96 offset:32256
	v_mfma_f32_32x32x16_bf16 v[32:47], v[148:151], v[108:111], v[32:47]
	v_add_f32_e32 v92, v78, v92
	v_add_f32_e32 v92, v79, v92
	v_add_f32_e32 v92, 0, v92
	v_cvt_pk_bf16_f32 v106, v76, v77
	v_cvt_pk_bf16_f32 v107, v78, v79
	s_mov_b64 s[18:19], 0xd620000
	v_lshl_add_u64 v[76:77], v[176:177], 0, s[18:19]
	s_add_i32 s18, s48, s42
	s_mov_b32 s19, m0
	s_mov_b32 m0, s18
	s_nop 0
	global_load_lds_dwordx4 v[76:77], off
	s_mov_b32 m0, s19
	s_mov_b64 s[18:19], 0x117e0000
	v_lshl_add_u64 v[76:77], v[178:179], 0, s[18:19]
	s_add_i32 s18, s45, s43
	s_mov_b32 s19, m0
	s_mov_b32 m0, s18
	s_nop 0
	global_load_lds_dwordx4 v[76:77], off
	s_mov_b32 m0, s19
	v_max_f32_e32 v76, v48, v49
	v_max3_f32 v77, v50, v51, v33
	v_max3_f32 v76, v76, v32, v34
	v_max3_f32 v76, v76, v35, v52
	v_max3_f32 v77, v77, v54, v55
	v_max3_f32 v76, v76, v53, v36
	v_max3_f32 v77, v77, v38, v39
	v_max3_f32 v76, v76, v37, v56
	v_max3_f32 v77, v77, v58, v59
	v_max3_f32 v76, v76, v57, v40
	v_max3_f32 v77, v77, v42, v43
	v_max3_f32 v76, v76, v41, v60
	v_max3_f32 v77, v77, v62, v63
	v_max3_f32 v76, v76, v61, v44
	v_max3_f32 v77, v77, v46, v47
	v_max3_f32 v76, v76, v45, v77
	v_mov_b32_e32 v77, v76
	s_nop 1
	v_permlane32_swap_b32_e32 v76, v77
	v_max_f32_e32 v76, v76, v77
	v_cmp_lt_f32_e32 vcc, s58, v76
	s_cmp_lg_u64 vcc, 0
	v_add_f32_e32 v234, v183, v92
	s_cselect_b64 s[18:19], -1, 0
	s_cbranch_vccnz .LBB0_88

.LBB0_101:
	v_max_f32_e32 v44, v80, v81
	v_max3_f32 v45, v82, v83, v65
	v_max3_f32 v44, v44, v64, v66
	v_max3_f32 v44, v44, v67, v84
	v_max3_f32 v45, v45, v86, v87
	v_max3_f32 v44, v44, v85, v68
	v_max3_f32 v45, v45, v70, v71
	v_max3_f32 v44, v44, v69, v88
	v_max3_f32 v45, v45, v90, v91
	v_max3_f32 v44, v44, v89, v72
	v_max3_f32 v45, v45, v74, v75
	v_max3_f32 v44, v44, v73, v92
	v_max3_f32 v45, v45, v94, v95
	v_max3_f32 v44, v44, v93, v76
	v_max3_f32 v45, v45, v78, v79
	v_max3_f32 v44, v44, v77, v45
	v_mov_b32_e32 v45, v44
	s_nop 1
	v_permlane32_swap_b32_e32 v44, v45
	v_max_f32_e32 v44, v44, v45
	v_cmp_lt_f32_e32 vcc, s58, v44
	s_cmp_lg_u64 vcc, 0
	v_add_f32_e32 v234, v234, v60
	s_cselect_b64 s[4:5], -1, 0
	s_cbranch_vccnz .LBB0_143

.LBB0_112:
	v_add_f32_e32 v234, v234, v72
	v_max_f32_e32 v72, v48, v49
	v_max3_f32 v73, v50, v51, v33
	v_max3_f32 v72, v72, v32, v34
	v_max3_f32 v72, v72, v35, v52
	v_max3_f32 v73, v73, v54, v55
	v_max3_f32 v72, v72, v53, v36
	v_max3_f32 v73, v73, v38, v39
	v_max3_f32 v72, v72, v37, v56
	v_max3_f32 v73, v73, v58, v59
	v_max3_f32 v72, v72, v57, v40
	v_max3_f32 v73, v73, v42, v43
	v_max3_f32 v72, v72, v41, v60
	v_max3_f32 v73, v73, v62, v63
	v_max3_f32 v72, v72, v61, v44
	v_max3_f32 v73, v73, v46, v47
	v_max3_f32 v72, v72, v45, v73
	v_mov_b32_e32 v73, v72
	s_nop 1
	v_permlane32_swap_b32_e32 v72, v73
	v_max_f32_e32 v72, v72, v73
	v_cmp_lt_f32_e32 vcc, s58, v72
	s_cmp_lg_u64 vcc, 0
	s_cselect_b64 s[18:19], -1, 0
	s_cbranch_vccnz .LBB0_146

.LBB0_150:
	v_mfma_f32_32x32x16_bf16 v[64:79], v[168:171], v[136:139], 0
	v_mfma_f32_32x32x16_bf16 v[80:95], v[176:179], v[136:139], 0
	v_add_u32_e32 v96, s47, v231
	ds_read_b64_tr_b16 v[136:137], v96 offset:24576
	ds_read_b64_tr_b16 v[138:139], v96 offset:25088
	v_add_f32_e32 v97, v48, v49
	v_add_f32_e32 v97, v50, v97
	v_add_f32_e32 v97, v51, v97
	v_add_f32_e32 v97, v52, v97
	v_add_f32_e32 v97, v53, v97
	v_cvt_pk_bf16_f32 v128, v48, v49
	v_cvt_pk_bf16_f32 v129, v50, v51
	s_waitcnt lgkmcnt(3)
	v_mfma_f32_32x32x16_bf16 v[80:95], v[172:175], v[132:135], v[80:95]
	ds_read_b64_tr_b16 v[168:169], v96 offset:28672
	ds_read_b64_tr_b16 v[170:171], v96 offset:29184
	s_waitcnt lgkmcnt(4)
	v_mfma_f32_32x32x16_bf16 v[64:79], v[164:167], v[132:135], v[64:79]
	v_add_f32_e32 v48, v54, v97
	v_add_f32_e32 v48, v55, v48
	v_add_f32_e32 v48, v56, v48
	v_add_f32_e32 v48, v57, v48
	v_cvt_pk_bf16_f32 v130, v52, v53
	v_cvt_pk_bf16_f32 v131, v54, v55
	ds_read_b64_tr_b16 v[132:133], v96 offset:25600
	ds_read_b64_tr_b16 v[134:135], v96 offset:26112
	v_add_f32_e32 v48, v58, v48
	v_add_f32_e32 v48, v59, v48
	v_add_f32_e32 v48, v60, v48
	v_add_f32_e32 v48, v61, v48
	v_cvt_pk_bf16_f32 v120, v56, v57
	v_cvt_pk_bf16_f32 v121, v58, v59
	v_mfma_f32_32x32x16_bf16 v[80:95], v[160:163], v[124:127], v[80:95]
	ds_read_b64_tr_b16 v[160:161], v96 offset:29696
	ds_read_b64_tr_b16 v[162:163], v96 offset:30208
	v_mfma_f32_32x32x16_bf16 v[64:79], v[156:159], v[124:127], v[64:79]
	v_add_f32_e32 v48, v62, v48
	v_add_f32_e32 v48, v63, v48
	v_add_f32_e32 v48, v32, v48
	v_add_f32_e32 v48, v33, v48
	v_cvt_pk_bf16_f32 v122, v60, v61
	v_cvt_pk_bf16_f32 v123, v62, v63
	ds_read_b64_tr_b16 v[124:125], v96 offset:26624
	ds_read_b64_tr_b16 v[126:127], v96 offset:27136
	v_add_f32_e32 v48, v34, v48
	v_add_f32_e32 v48, v35, v48
	v_add_f32_e32 v48, v36, v48
	v_add_f32_e32 v48, v37, v48
	v_cvt_pk_bf16_f32 v112, v32, v33
	v_cvt_pk_bf16_f32 v113, v34, v35
	v_mfma_f32_32x32x16_bf16 v[80:95], v[152:155], v[116:119], v[80:95]
	ds_read_b64_tr_b16 v[152:153], v96 offset:30720
	ds_read_b64_tr_b16 v[154:155], v96 offset:31232
	v_mfma_f32_32x32x16_bf16 v[64:79], v[148:151], v[116:119], v[64:79]
	v_add_f32_e32 v32, v38, v48
	v_add_f32_e32 v32, v39, v32
	v_add_f32_e32 v32, v40, v32
	v_add_f32_e32 v32, v41, v32
	v_cvt_pk_bf16_f32 v114, v36, v37
	v_cvt_pk_bf16_f32 v115, v38, v39
	ds_read_b64_tr_b16 v[116:117], v96 offset:27648
	ds_read_b64_tr_b16 v[118:119], v96 offset:28160
	v_add_f32_e32 v32, v42, v32
	v_add_f32_e32 v32, v43, v32
	v_add_f32_e32 v32, v44, v32
	v_add_f32_e32 v32, v45, v32
	v_cvt_pk_bf16_f32 v104, v40, v41
	v_cvt_pk_bf16_f32 v105, v42, v43
	v_mfma_f32_32x32x16_bf16 v[80:95], v[144:147], v[108:111], v[80:95]
	ds_read_b64_tr_b16 v[144:145], v96 offset:31744
	ds_read_b64_tr_b16 v[146:147], v96 offset:32256
	v_mfma_f32_32x32x16_bf16 v[64:79], v[140:143], v[108:111], v[64:79]
	v_add_f32_e32 v32, v46, v32
	v_add_f32_e32 v32, v47, v32
	v_add_f32_e32 v96, 0, v32
	v_cvt_pk_bf16_f32 v106, v44, v45
	v_cvt_pk_bf16_f32 v107, v46, v47
	v_or_b32_e32 v32, 0xe0, v226
	v_or_b32_e32 v33, 0xc0, v226
	v_cmp_le_i32_e32 vcc, v32, v228
	v_or_b32_e32 v34, 0xc2, v226
	v_or_b32_e32 v35, 0xc3, v226
	s_nop 1
	v_cndmask_b32_e32 v32, v213, v64, vcc
	v_cmp_lt_i32_e32 vcc, v33, v228
	v_or_b32_e32 v36, 0xc8, v226
	v_or_b32_e32 v37, 0xc9, v226
	v_cndmask_b32_e32 v49, v213, v81, vcc
	v_cmp_le_i32_e32 vcc, v33, v228
	v_or_b32_e32 v33, 0xe1, v226
	v_or_b32_e32 v38, 0xca, v226
	v_cndmask_b32_e32 v48, v213, v80, vcc
	v_cmp_le_i32_e32 vcc, v33, v228
	v_or_b32_e32 v39, 0xcb, v226
	v_or_b32_e32 v40, 0xd0, v226
	v_cndmask_b32_e32 v33, v213, v65, vcc
	v_cmp_le_i32_e32 vcc, v34, v228
	v_or_b32_e32 v34, 0xe2, v226
	v_or_b32_e32 v41, 0xd1, v226
	v_cndmask_b32_e32 v50, v213, v82, vcc
	v_cmp_le_i32_e32 vcc, v34, v228
	v_or_b32_e32 v42, 0xd2, v226
	v_or_b32_e32 v43, 0xd3, v226
	v_cndmask_b32_e32 v34, v213, v66, vcc
	v_cmp_le_i32_e32 vcc, v35, v228
	v_or_b32_e32 v35, 0xe3, v226
	v_or_b32_e32 v44, 0xd8, v226
	v_cndmask_b32_e32 v51, v213, v83, vcc
	v_cmp_le_i32_e32 vcc, v35, v228
	v_or_b32_e32 v45, 0xd9, v226
	v_max_f32_e32 v64, v49, v49
	v_cndmask_b32_e32 v35, v213, v67, vcc
	v_cmp_le_i32_e32 vcc, v36, v228
	v_or_b32_e32 v36, 0xe8, v226
	v_max_f32_e32 v65, v48, v48
	v_cndmask_b32_e32 v52, v213, v84, vcc
	v_cmp_le_i32_e32 vcc, v36, v228
	v_max_f32_e32 v64, v65, v64
	v_or_b32_e32 v46, 0xda, v226
	v_cndmask_b32_e32 v36, v213, v68, vcc
	v_cmp_le_i32_e32 vcc, v37, v228
	v_or_b32_e32 v37, 0xe9, v226
	v_max3_f32 v65, v50, v51, v33
	v_cndmask_b32_e32 v53, v213, v85, vcc
	v_cmp_le_i32_e32 vcc, v37, v228
	v_max3_f32 v64, v64, v32, v34
	v_max3_f32 v64, v64, v35, v52
	v_cndmask_b32_e32 v37, v213, v69, vcc
	v_cmp_le_i32_e32 vcc, v38, v228
	v_or_b32_e32 v38, 0xea, v226
	v_or_b32_e32 v47, 0xdb, v226
	v_cndmask_b32_e32 v54, v213, v86, vcc
	v_cmp_le_i32_e32 vcc, v38, v228
	v_max3_f32 v64, v64, v53, v36
	s_nop 0
	v_cndmask_b32_e32 v38, v213, v70, vcc
	v_cmp_le_i32_e32 vcc, v39, v228
	v_or_b32_e32 v39, 0xeb, v226
	s_nop 0
	v_cndmask_b32_e32 v55, v213, v87, vcc
	v_cmp_le_i32_e32 vcc, v39, v228
	v_max3_f32 v65, v65, v54, v55
	s_nop 0
	v_cndmask_b32_e32 v39, v213, v71, vcc
	v_cmp_le_i32_e32 vcc, v40, v228
	v_or_b32_e32 v40, 0xf0, v226
	v_max3_f32 v65, v65, v38, v39
	v_cndmask_b32_e32 v56, v213, v88, vcc
	v_cmp_le_i32_e32 vcc, v40, v228
	v_max3_f32 v64, v64, v37, v56
	s_nop 0
	v_cndmask_b32_e32 v40, v213, v72, vcc
	v_cmp_le_i32_e32 vcc, v41, v228
	v_or_b32_e32 v41, 0xf1, v226
	s_nop 0
	v_cndmask_b32_e32 v57, v213, v89, vcc
	v_cmp_le_i32_e32 vcc, v41, v228
	v_max3_f32 v64, v64, v57, v40
	s_nop 0
	v_cndmask_b32_e32 v41, v213, v73, vcc
	v_cmp_le_i32_e32 vcc, v42, v228
	v_or_b32_e32 v42, 0xf2, v226
	s_nop 0
	v_cndmask_b32_e32 v58, v213, v90, vcc
	v_cmp_le_i32_e32 vcc, v42, v228
	s_nop 1
	v_cndmask_b32_e32 v42, v213, v74, vcc
	v_cmp_le_i32_e32 vcc, v43, v228
	v_or_b32_e32 v43, 0xf3, v226
	s_nop 0
	v_cndmask_b32_e32 v59, v213, v91, vcc
	v_cmp_le_i32_e32 vcc, v43, v228
	v_max3_f32 v65, v65, v58, v59
	s_nop 0
	v_cndmask_b32_e32 v43, v213, v75, vcc
	v_cmp_le_i32_e32 vcc, v44, v228
	v_or_b32_e32 v44, 0xf8, v226
	v_max3_f32 v65, v65, v42, v43
	v_cndmask_b32_e32 v60, v213, v92, vcc
	v_cmp_le_i32_e32 vcc, v44, v228
	v_max3_f32 v64, v64, v41, v60
	s_nop 0
	v_cndmask_b32_e32 v44, v213, v76, vcc
	v_cmp_le_i32_e32 vcc, v45, v228
	v_or_b32_e32 v45, 0xf9, v226
	s_nop 0
	v_cndmask_b32_e32 v61, v213, v93, vcc
	v_cmp_le_i32_e32 vcc, v45, v228
	v_max3_f32 v66, v64, v61, v44
	v_add_f32_e32 v64, v234, v96
	v_cndmask_b32_e32 v45, v213, v77, vcc
	v_cmp_le_i32_e32 vcc, v46, v228
	v_or_b32_e32 v46, 0xfa, v226
	s_nop 0
	v_cndmask_b32_e32 v62, v213, v94, vcc
	v_cmp_le_i32_e32 vcc, v46, v228
	s_nop 1
	v_cndmask_b32_e32 v46, v213, v78, vcc
	v_cmp_le_i32_e32 vcc, v47, v228
	v_or_b32_e32 v47, 0xfb, v226
	s_nop 0
	v_cndmask_b32_e32 v63, v213, v95, vcc
	v_cmp_le_i32_e32 vcc, v47, v228
	v_max3_f32 v65, v65, v62, v63
	s_nop 0
	v_cndmask_b32_e32 v47, v213, v79, vcc
	v_max3_f32 v65, v65, v46, v47
	v_max3_f32 v65, v66, v45, v65
	v_mov_b32_e32 v66, v65
	s_nop 1
	v_permlane32_swap_b32_e32 v65, v66
	v_max_f32_e32 v65, v65, v66
	v_cmp_lt_f32_e32 vcc, s58, v65
	s_cmp_lg_u64 vcc, 0
	s_cselect_b64 s[4:5], -1, 0
	s_cbranch_vccnz .LBB0_155
